# combo6 + attention loop-edge rotation (loop-carried updates ahead of the closing barriers) + waves 0-3 skip the fully masked final step and drain
# speedup vs baseline: 1.0019x; 1.0019x over previous
.LBB0_647:
	s_mov_b32 s25, s24
	s_mov_b32 s1, s2
	v_lshl_add_u32 v214, s27, 1, v248
	ds_read_b64_tr_b16 v[66:67], v214 offset:24576
	ds_read_b64_tr_b16 v[68:69], v214 offset:25088
	v_mfma_f32_32x32x16_bf16 v[128:143], v[204:207], v[172:175], 0
	v_add_f32_e32 v65, v96, v97
	v_add_f32_e32 v65, v98, v65
	v_add_f32_e32 v65, v99, v65
	v_add_f32_e32 v65, v100, v65
	v_add_f32_e32 v65, v101, v65
	v_cvt_pk_bf16_f32 v160, v96, v97
	v_cvt_pk_bf16_f32 v161, v98, v99
	ds_read_b64_tr_b16 v[70:71], v214 offset:28672
	ds_read_b64_tr_b16 v[72:73], v214 offset:29184
	v_mfma_f32_32x32x16_bf16 v[112:127], v[200:203], v[172:175], 0
	v_add_f32_e32 v65, v102, v65
	v_add_f32_e32 v65, v103, v65
	v_add_f32_e32 v65, v104, v65
	v_add_f32_e32 v65, v105, v65
	v_cvt_pk_bf16_f32 v162, v100, v101
	v_cvt_pk_bf16_f32 v163, v102, v103
	ds_read_b64_tr_b16 v[74:75], v214 offset:25600
	ds_read_b64_tr_b16 v[76:77], v214 offset:26112
	v_mfma_f32_32x32x16_bf16 v[128:143], v[196:199], v[168:171], v[128:143]
	v_add_f32_e32 v65, v106, v65
	v_add_f32_e32 v65, v107, v65
	v_add_f32_e32 v65, v108, v65
	v_add_f32_e32 v65, v109, v65
	v_cvt_pk_bf16_f32 v152, v104, v105
	v_cvt_pk_bf16_f32 v153, v106, v107
	ds_read_b64_tr_b16 v[96:97], v214 offset:29696
	ds_read_b64_tr_b16 v[98:99], v214 offset:30208
	v_mfma_f32_32x32x16_bf16 v[112:127], v[192:195], v[168:171], v[112:127]
	v_add_f32_e32 v65, v110, v65
	v_add_f32_e32 v65, v111, v65
	v_add_f32_e32 v65, v80, v65
	v_add_f32_e32 v65, v81, v65
	v_cvt_pk_bf16_f32 v154, v108, v109
	v_cvt_pk_bf16_f32 v155, v110, v111
	ds_read_b64_tr_b16 v[100:101], v214 offset:26624
	ds_read_b64_tr_b16 v[102:103], v214 offset:27136
	v_mfma_f32_32x32x16_bf16 v[128:143], v[188:191], v[164:167], v[128:143]
	v_add_f32_e32 v65, v82, v65
	v_add_f32_e32 v65, v83, v65
	v_add_f32_e32 v65, v84, v65
	v_add_f32_e32 v65, v85, v65
	v_cvt_pk_bf16_f32 v148, v80, v81
	v_cvt_pk_bf16_f32 v149, v82, v83
	ds_read_b64_tr_b16 v[104:105], v214 offset:30720
	ds_read_b64_tr_b16 v[106:107], v214 offset:31232
	v_mfma_f32_32x32x16_bf16 v[112:127], v[184:187], v[164:167], v[112:127]
	v_add_f32_e32 v65, v86, v65
	v_add_f32_e32 v65, v87, v65
	v_add_f32_e32 v65, v88, v65
	v_add_f32_e32 v65, v89, v65
	v_cvt_pk_bf16_f32 v150, v84, v85
	v_cvt_pk_bf16_f32 v151, v86, v87
	ds_read_b64_tr_b16 v[108:109], v214 offset:27648
	ds_read_b64_tr_b16 v[110:111], v214 offset:28160
	v_mfma_f32_32x32x16_bf16 v[128:143], v[180:183], v[156:159], v[128:143]
	v_add_f32_e32 v65, v90, v65
	v_add_f32_e32 v65, v91, v65
	v_add_f32_e32 v65, v92, v65
	v_add_f32_e32 v65, v93, v65
	v_cvt_pk_bf16_f32 v144, v88, v89
	v_cvt_pk_bf16_f32 v145, v90, v91
	ds_read_b64_tr_b16 v[86:87], v214 offset:31744
	ds_read_b64_tr_b16 v[88:89], v214 offset:32256
	v_mfma_f32_32x32x16_bf16 v[112:127], v[176:179], v[156:159], v[112:127]
	v_add_f32_e32 v65, v94, v65
	v_add_f32_e32 v65, v95, v65
	v_add_f32_e32 v65, 0, v65
	v_cvt_pk_bf16_f32 v146, v92, v93
	v_cvt_pk_bf16_f32 v147, v94, v95
	s_add_i32 s2, s2, s69
	v_lshl_add_u64 v[78:79], v[212:213], 0, s[16:17]
	s_mov_b32 s24, m0
	s_mov_b32 m0, s2
	s_nop 0
	global_load_lds_dwordx4 v[78:79], off
	s_mov_b32 m0, s24
	s_lshl_b32 s2, s25, 1
	v_lshl_add_u64 v[78:79], v[210:211], 0, s[16:17]
	s_add_i32 s24, s2, s72
	s_mov_b32 s27, m0
	s_mov_b32 m0, s24
	s_nop 0
	global_load_lds_dwordx4 v[78:79], off
	s_mov_b32 m0, s27
	v_lshl_add_u64 v[78:79], v[208:209], 0, s[16:17]
	s_add_i32 s2, s2, s73
	s_mov_b32 s24, m0
	s_mov_b32 m0, s2
	s_nop 0
	global_load_lds_dwordx4 v[78:79], off
	s_mov_b32 m0, s24
	s_waitcnt lgkmcnt(14)
	v_mfma_f32_32x32x16_bf16 v[16:31], v[160:163], v[66:69], v[16:31]
	ds_read_b64_tr_b16 v[90:91], v214 offset:32768
	ds_read_b64_tr_b16 v[92:93], v214 offset:33280
	v_exp_f32_e32 v128, v128
	v_exp_f32_e32 v129, v129
	s_waitcnt lgkmcnt(14)
	v_mfma_f32_32x32x16_bf16 v[48:63], v[160:163], v[70:73], v[48:63]
	ds_read_b64_tr_b16 v[188:189], v214 offset:36864
	ds_read_b64_tr_b16 v[190:191], v214 offset:37376
	v_exp_f32_e32 v130, v130
	v_exp_f32_e32 v131, v131
	v_add_u32_e32 v66, s25, v246
	ds_read_b128 v[82:85], v66
	ds_read_b128 v[78:81], v66 offset:512
	s_waitcnt lgkmcnt(14)
	v_mfma_f32_32x32x16_bf16 v[16:31], v[152:155], v[74:77], v[16:31]
	ds_read_b64_tr_b16 v[192:193], v214 offset:33792
	ds_read_b64_tr_b16 v[194:195], v214 offset:34304
	v_exp_f32_e32 v132, v132
	v_exp_f32_e32 v133, v133
	ds_read_b128 v[184:187], v66 offset:2048
	ds_read_b128 v[176:179], v66 offset:2560
	v_mfma_f32_32x32x16_bf16 v[48:63], v[152:155], v[96:99], v[48:63]
	ds_read_b64_tr_b16 v[196:197], v214 offset:37888
	ds_read_b64_tr_b16 v[198:199], v214 offset:38400
	v_exp_f32_e32 v134, v134
	v_exp_f32_e32 v135, v135
	ds_read_b128 v[180:183], v66 offset:4096
	ds_read_b128 v[70:73], v66 offset:4608
	s_waitcnt lgkmcnt(14)
	v_mfma_f32_32x32x16_bf16 v[16:31], v[148:151], v[100:103], v[16:31]
	ds_read_b64_tr_b16 v[94:95], v214 offset:34816
	ds_read_b64_tr_b16 v[96:97], v214 offset:35328
	v_exp_f32_e32 v136, v136
	v_exp_f32_e32 v137, v137
	ds_read_b128 v[74:77], v66 offset:6144
	ds_read_b128 v[66:69], v66 offset:6656
	v_mfma_f32_32x32x16_bf16 v[48:63], v[148:151], v[104:107], v[48:63]
	ds_read_b64_tr_b16 v[98:99], v214 offset:38912
	ds_read_b64_tr_b16 v[100:101], v214 offset:39424
	v_exp_f32_e32 v138, v138
	v_exp_f32_e32 v139, v139
	v_mfma_f32_32x32x16_bf16 v[16:31], v[144:147], v[108:111], v[16:31]
	ds_read_b64_tr_b16 v[102:103], v214 offset:35840
	ds_read_b64_tr_b16 v[104:105], v214 offset:36352
	v_exp_f32_e32 v140, v140
	v_exp_f32_e32 v141, v141
	v_mfma_f32_32x32x16_bf16 v[48:63], v[144:147], v[86:89], v[48:63]
	ds_read_b64_tr_b16 v[106:107], v214 offset:39936
	ds_read_b64_tr_b16 v[108:109], v214 offset:40448
	v_exp_f32_e32 v142, v142
	v_exp_f32_e32 v143, v143
	s_waitcnt lgkmcnt(14)
	v_mfma_f32_32x32x16_bf16 v[0:15], v[160:163], v[90:93], v[0:15]
	v_exp_f32_e32 v112, v112
	v_exp_f32_e32 v113, v113
	v_mfma_f32_32x32x16_bf16 v[32:47], v[160:163], v[188:191], v[32:47]
	v_exp_f32_e32 v114, v114
	v_exp_f32_e32 v115, v115
	v_mfma_f32_32x32x16_bf16 v[0:15], v[152:155], v[192:195], v[0:15]
	v_exp_f32_e32 v116, v116
	v_exp_f32_e32 v117, v117
	s_waitcnt lgkmcnt(12)
	v_mfma_f32_32x32x16_bf16 v[32:47], v[152:155], v[196:199], v[32:47]
	v_exp_f32_e32 v118, v118
	v_exp_f32_e32 v119, v119
	s_waitcnt lgkmcnt(8)
	v_mfma_f32_32x32x16_bf16 v[0:15], v[148:151], v[94:97], v[0:15]
	v_exp_f32_e32 v120, v120
	v_exp_f32_e32 v121, v121
	s_waitcnt lgkmcnt(4)
	v_mfma_f32_32x32x16_bf16 v[32:47], v[148:151], v[98:101], v[32:47]
	v_exp_f32_e32 v122, v122
	v_exp_f32_e32 v123, v123
	s_waitcnt lgkmcnt(2)
	v_mfma_f32_32x32x16_bf16 v[0:15], v[144:147], v[102:105], v[0:15]
	v_exp_f32_e32 v124, v124
	v_exp_f32_e32 v125, v125
	s_waitcnt lgkmcnt(0)
	v_mfma_f32_32x32x16_bf16 v[32:47], v[144:147], v[106:109], v[32:47]
	v_exp_f32_e32 v126, v126
	v_exp_f32_e32 v127, v127
	s_add_i32 s2, s25, 0x2000
	s_cmpk_lg_i32 s25, 0x4000
	s_cselect_b32 s2, s2, 0
	s_waitcnt vmcnt(3) lgkmcnt(0)
	s_barrier
	v_lshl_add_u32 v214, s1, 1, v248
	ds_read_b64_tr_b16 v[188:189], v214 offset:24576
	ds_read_b64_tr_b16 v[190:191], v214 offset:25088
	v_mfma_f32_32x32x16_bf16 v[96:111], v[82:85], v[172:175], 0
	v_add_f32_e32 v86, v128, v129
	v_add_f32_e32 v86, v130, v86
	v_add_f32_e32 v86, v131, v86
	v_add_f32_e32 v86, v132, v86
	v_add_f32_e32 v86, v133, v86
	v_cvt_pk_bf16_f32 v160, v128, v129
	v_cvt_pk_bf16_f32 v161, v130, v131
	ds_read_b64_tr_b16 v[128:129], v214 offset:28672
	ds_read_b64_tr_b16 v[130:131], v214 offset:29184
	v_add_f32_e32 v82, v134, v86
	v_add_f32_e32 v82, v135, v82
	v_add_f32_e32 v82, v136, v82
	v_add_f32_e32 v144, v137, v82
	v_mfma_f32_32x32x16_bf16 v[80:95], v[78:81], v[172:175], 0
	v_cvt_pk_bf16_f32 v162, v132, v133
	v_cvt_pk_bf16_f32 v163, v134, v135
	ds_read_b64_tr_b16 v[132:133], v214 offset:25600
	ds_read_b64_tr_b16 v[134:135], v214 offset:26112
	v_mfma_f32_32x32x16_bf16 v[96:111], v[184:187], v[168:171], v[96:111]
	v_add_f32_e32 v78, v138, v144
	v_add_f32_e32 v78, v139, v78
	v_add_f32_e32 v78, v140, v78
	v_add_f32_e32 v78, v141, v78
	v_cvt_pk_bf16_f32 v152, v136, v137
	v_cvt_pk_bf16_f32 v153, v138, v139
	ds_read_b64_tr_b16 v[136:137], v214 offset:29696
	ds_read_b64_tr_b16 v[138:139], v214 offset:30208
	v_mfma_f32_32x32x16_bf16 v[80:95], v[176:179], v[168:171], v[80:95]
	v_add_f32_e32 v78, v142, v78
	v_add_f32_e32 v78, v143, v78
	v_add_f32_e32 v78, v112, v78
	v_add_f32_e32 v78, v113, v78
	v_cvt_pk_bf16_f32 v154, v140, v141
	v_cvt_pk_bf16_f32 v155, v142, v143
	ds_read_b64_tr_b16 v[140:141], v214 offset:26624
	ds_read_b64_tr_b16 v[142:143], v214 offset:27136
	v_mfma_f32_32x32x16_bf16 v[96:111], v[180:183], v[164:167], v[96:111]
	v_add_f32_e32 v78, v114, v78
	v_add_f32_e32 v78, v115, v78
	v_add_f32_e32 v78, v116, v78
	v_add_f32_e32 v78, v117, v78
	v_cvt_pk_bf16_f32 v148, v112, v113
	v_cvt_pk_bf16_f32 v149, v114, v115
	ds_read_b64_tr_b16 v[112:113], v214 offset:30720
	ds_read_b64_tr_b16 v[114:115], v214 offset:31232
	v_mfma_f32_32x32x16_bf16 v[80:95], v[70:73], v[164:167], v[80:95]
	v_add_f32_e32 v78, v118, v78
	v_add_f32_e32 v78, v119, v78
	v_add_f32_e32 v78, v120, v78
	v_add_f32_e32 v78, v121, v78
	v_cvt_pk_bf16_f32 v150, v116, v117
	v_cvt_pk_bf16_f32 v151, v118, v119
	ds_read_b64_tr_b16 v[70:71], v214 offset:27648
	ds_read_b64_tr_b16 v[72:73], v214 offset:28160
	v_mfma_f32_32x32x16_bf16 v[96:111], v[74:77], v[156:159], v[96:111]
	v_add_f32_e32 v78, v122, v78
	v_add_f32_e32 v78, v123, v78
	v_add_f32_e32 v78, v124, v78
	v_add_f32_e32 v78, v125, v78
	v_cvt_pk_bf16_f32 v144, v120, v121
	v_cvt_pk_bf16_f32 v145, v122, v123
	ds_read_b64_tr_b16 v[74:75], v214 offset:31744
	ds_read_b64_tr_b16 v[76:77], v214 offset:32256
	v_mfma_f32_32x32x16_bf16 v[80:95], v[66:69], v[156:159], v[80:95]
	v_add_f32_e32 v78, v126, v78
	v_add_f32_e32 v78, v127, v78
	v_add_f32_e32 v78, 0, v78
	v_cvt_pk_bf16_f32 v146, v124, v125
	v_cvt_pk_bf16_f32 v147, v126, v127
	s_add_i32 s1, s25, s69
	s_mov_b32 s24, m0
	s_mov_b32 m0, s1
	s_nop 0
	global_load_lds_dwordx4 v[212:213], off
	s_mov_b32 m0, s24
	s_lshl_b32 s1, s2, 1
	s_add_i32 s24, s1, s72
	s_mov_b32 s27, m0
	s_mov_b32 m0, s24
	s_nop 0
	global_load_lds_dwordx4 v[210:211], off
	s_mov_b32 m0, s27
	s_add_i32 s1, s1, s73
	s_mov_b32 s24, m0
	s_mov_b32 m0, s1
	s_nop 0
	global_load_lds_dwordx4 v[208:209], off
	s_mov_b32 m0, s24
	s_add_i32 s8, s8, 2
	s_waitcnt lgkmcnt(14)
	v_mfma_f32_32x32x16_bf16 v[16:31], v[160:163], v[188:191], v[16:31]
	ds_read_b64_tr_b16 v[66:67], v214 offset:32768
	ds_read_b64_tr_b16 v[68:69], v214 offset:33280
	v_exp_f32_e32 v96, v96
	v_exp_f32_e32 v97, v97
	s_waitcnt lgkmcnt(14)
	v_mfma_f32_32x32x16_bf16 v[48:63], v[160:163], v[128:131], v[48:63]
	ds_read_b64_tr_b16 v[116:117], v214 offset:36864
	ds_read_b64_tr_b16 v[118:119], v214 offset:37376
	v_exp_f32_e32 v98, v98
	v_exp_f32_e32 v99, v99
	v_add_u32_e32 v79, s2, v246
	ds_read_b128 v[204:207], v79
	ds_read_b128 v[200:203], v79 offset:512
	s_waitcnt lgkmcnt(14)
	v_mfma_f32_32x32x16_bf16 v[16:31], v[152:155], v[132:135], v[16:31]
	ds_read_b64_tr_b16 v[120:121], v214 offset:33792
	ds_read_b64_tr_b16 v[122:123], v214 offset:34304
	v_exp_f32_e32 v100, v100
	v_exp_f32_e32 v101, v101
	ds_read_b128 v[196:199], v79 offset:2048
	ds_read_b128 v[192:195], v79 offset:2560
	v_mfma_f32_32x32x16_bf16 v[48:63], v[152:155], v[136:139], v[48:63]
	ds_read_b64_tr_b16 v[124:125], v214 offset:37888
	ds_read_b64_tr_b16 v[126:127], v214 offset:38400
	v_exp_f32_e32 v102, v102
	v_exp_f32_e32 v103, v103
	ds_read_b128 v[188:191], v79 offset:4096
	ds_read_b128 v[184:187], v79 offset:4608
	s_waitcnt lgkmcnt(14)
	v_mfma_f32_32x32x16_bf16 v[16:31], v[148:151], v[140:143], v[16:31]
	ds_read_b64_tr_b16 v[128:129], v214 offset:34816
	ds_read_b64_tr_b16 v[130:131], v214 offset:35328
	v_exp_f32_e32 v104, v104
	v_exp_f32_e32 v105, v105
	ds_read_b128 v[180:183], v79 offset:6144
	ds_read_b128 v[176:179], v79 offset:6656
	v_mfma_f32_32x32x16_bf16 v[48:63], v[148:151], v[112:115], v[48:63]
	ds_read_b64_tr_b16 v[132:133], v214 offset:38912
	ds_read_b64_tr_b16 v[134:135], v214 offset:39424
	v_exp_f32_e32 v106, v106
	v_exp_f32_e32 v107, v107
	v_mfma_f32_32x32x16_bf16 v[16:31], v[144:147], v[70:73], v[16:31]
	ds_read_b64_tr_b16 v[112:113], v214 offset:35840
	ds_read_b64_tr_b16 v[114:115], v214 offset:36352
	v_exp_f32_e32 v108, v108
	v_exp_f32_e32 v109, v109
	v_mfma_f32_32x32x16_bf16 v[48:63], v[144:147], v[74:77], v[48:63]
	ds_read_b64_tr_b16 v[70:71], v214 offset:39936
	ds_read_b64_tr_b16 v[72:73], v214 offset:40448
	v_exp_f32_e32 v110, v110
	v_exp_f32_e32 v111, v111
	s_waitcnt lgkmcnt(14)
	v_mfma_f32_32x32x16_bf16 v[0:15], v[160:163], v[66:69], v[0:15]
	v_exp_f32_e32 v80, v80
	v_exp_f32_e32 v81, v81
	v_mfma_f32_32x32x16_bf16 v[32:47], v[160:163], v[116:119], v[32:47]
	v_exp_f32_e32 v82, v82
	v_exp_f32_e32 v83, v83
	v_mfma_f32_32x32x16_bf16 v[0:15], v[152:155], v[120:123], v[0:15]
	v_exp_f32_e32 v84, v84
	v_exp_f32_e32 v85, v85
	s_waitcnt lgkmcnt(12)
	v_mfma_f32_32x32x16_bf16 v[32:47], v[152:155], v[124:127], v[32:47]
	v_exp_f32_e32 v86, v86
	v_exp_f32_e32 v87, v87
	s_waitcnt lgkmcnt(8)
	v_mfma_f32_32x32x16_bf16 v[0:15], v[148:151], v[128:131], v[0:15]
	v_exp_f32_e32 v88, v88
	v_exp_f32_e32 v89, v89
	s_waitcnt lgkmcnt(4)
	v_mfma_f32_32x32x16_bf16 v[32:47], v[148:151], v[132:135], v[32:47]
	v_exp_f32_e32 v90, v90
	v_exp_f32_e32 v91, v91
	s_waitcnt lgkmcnt(2)
	v_mfma_f32_32x32x16_bf16 v[0:15], v[144:147], v[112:115], v[0:15]
	v_exp_f32_e32 v92, v92
	v_exp_f32_e32 v93, v93
	s_waitcnt lgkmcnt(0)
	v_mfma_f32_32x32x16_bf16 v[32:47], v[144:147], v[70:73], v[32:47]
	v_exp_f32_e32 v94, v94
	v_exp_f32_e32 v95, v95
	s_add_i32 s1, s2, 0x2000
	v_add_f32_e32 v64, v64, v65
	s_cmpk_lg_i32 s2, 0x4000
	v_lshl_add_u64 v[208:209], v[208:209], 0, s[12:13]
	v_lshl_add_u64 v[210:211], v[210:211], 0, s[12:13]
	v_lshl_add_u64 v[212:213], v[212:213], 0, s[12:13]
	s_mov_b32 s27, s25
	s_cselect_b32 s24, s1, 0
	s_cmp_ge_i32 s8, s0
	v_add_f32_e32 v64, v64, v78
	s_waitcnt vmcnt(3) lgkmcnt(0)
	s_barrier
	s_cbranch_scc0 .LBB0_647
	s_add_i32 s0, s8, 1
	s_cmp_ge_i32 s0, s26
	s_mov_b64 s[0:1], -1
	s_cbranch_scc0 .LBB0_650

.Lmy_t_last:
.Lmy_t_done:
	s_bitcmp1_b32 s85, 8
	s_cbranch_scc1 .Lmy_fs_go
	v_mov_b32_e32 v65, v64
	s_nop 1
	v_permlane32_swap_b32_e32 v64, v65
	v_cmp_gt_u32_e32 vcc, 32, v242
	s_branch .Lmy_fs_join

.Lmy_fs_join:
	s_and_saveexec_b64 s[0:1], vcc
	v_lshl_add_u32 v66, v242, 2, s70
	v_add_f32_e32 v64, v64, v65
	ds_write_b32 v66, v64 offset:128
	s_or_b64 exec, exec, s[0:1]
	s_waitcnt lgkmcnt(0)
	v_lshl_add_u32 v72, v244, 4, s70
	ds_read_b128 v[64:67], v72 offset:128
	ds_read_b128 v[68:71], v72 offset:160
	s_lshl_b64 s[0:1], s[48:49], 12
	s_add_u32 s0, s6, s0
	s_addc_u32 s1, s7, s1
	s_waitcnt lgkmcnt(1)
	v_rcp_f32_e32 v73, v64
	v_rcp_f32_e32 v74, v65
	v_rcp_f32_e32 v75, v66
	v_rcp_f32_e32 v76, v67
	s_waitcnt lgkmcnt(0)
	v_rcp_f32_e32 v77, v68
	ds_read_b128 v[64:67], v72 offset:192
	v_rcp_f32_e32 v78, v69
	v_rcp_f32_e32 v79, v70
	v_rcp_f32_e32 v80, v71
	ds_read_b128 v[68:71], v72 offset:224
	s_waitcnt lgkmcnt(1)
	v_rcp_f32_e32 v64, v64
	v_rcp_f32_e32 v65, v65
	v_rcp_f32_e32 v66, v66
	v_rcp_f32_e32 v67, v67
	s_waitcnt lgkmcnt(0)
	v_rcp_f32_e32 v68, v68
	v_rcp_f32_e32 v69, v69
	v_rcp_f32_e32 v70, v70
	v_rcp_f32_e32 v71, v71
	s_add_u32 s0, s0, s50
	s_addc_u32 s1, s1, s51
	s_bitcmp1_b32 s19, 0
	v_lshrrev_b32_e32 v230, 3, v242
	s_cselect_b64 s[24:25], -1, 0
	v_lshlrev_b32_e32 v72, 9, v244
	v_lshlrev_b32_e32 v81, 1, v243
	v_or_b32_e32 v185, 8, v230
	v_or_b32_e32 v177, 16, v230
	v_or_b32_e32 v171, 24, v230
	v_add3_u32 v166, s74, v72, v81
	s_mov_b64 s[52:53], -1
	s_and_b64 vcc, exec, s[24:25]
	v_lshlrev_b32_e32 v84, 12, v230
	v_mul_f32_e32 v246, v16, v73
	v_mul_f32_e32 v245, v48, v73
	v_mul_f32_e32 v244, v17, v74
	v_mul_f32_e32 v243, v49, v74
	v_mul_f32_e32 v242, v18, v75
	v_mul_f32_e32 v233, v50, v75
	v_mul_f32_e32 v232, v19, v76
	v_mul_f32_e32 v231, v51, v76
	v_mul_f32_e32 v229, v20, v77
	v_mul_f32_e32 v228, v52, v77
	v_mul_f32_e32 v227, v21, v78
	v_mul_f32_e32 v226, v53, v78
	v_mul_f32_e32 v225, v22, v79
	v_mul_f32_e32 v224, v54, v79
	v_mul_f32_e32 v219, v23, v80
	v_mul_f32_e32 v218, v55, v80
	v_mul_f32_e32 v217, v24, v64
	v_mul_f32_e32 v216, v56, v64
	v_mul_f32_e32 v215, v25, v65
	v_mul_f32_e32 v214, v57, v65
	v_mul_f32_e32 v213, v26, v66
	v_mul_f32_e32 v212, v58, v66
	v_mul_f32_e32 v211, v27, v67
	v_mul_f32_e32 v210, v59, v67
	v_mul_f32_e32 v209, v28, v68
	v_mul_f32_e32 v208, v60, v68
	v_mul_f32_e32 v207, v29, v69
	v_mul_f32_e32 v206, v61, v69
	v_mul_f32_e32 v205, v30, v70
	v_mul_f32_e32 v204, v62, v70
	v_mul_f32_e32 v203, v31, v71
	v_mul_f32_e32 v202, v63, v71
	v_lshlrev_b32_e32 v90, 12, v185
	v_lshlrev_b32_e32 v88, 12, v177
	v_lshlrev_b32_e32 v86, 12, v171
	v_mul_f32_e32 v201, v0, v73
	v_mul_f32_e32 v200, v32, v73
	v_mul_f32_e32 v199, v1, v74
	v_mul_f32_e32 v198, v33, v74
	v_mul_f32_e32 v197, v2, v75
	v_mul_f32_e32 v196, v34, v75
	v_mul_f32_e32 v195, v3, v76
	v_mul_f32_e32 v194, v35, v76
	v_mul_f32_e32 v193, v4, v77
	v_mul_f32_e32 v192, v36, v77
	v_mul_f32_e32 v191, v5, v78
	v_mul_f32_e32 v190, v37, v78
	v_mul_f32_e32 v189, v6, v79
	v_mul_f32_e32 v188, v38, v79
	v_mul_f32_e32 v187, v7, v80
	v_mul_f32_e32 v186, v39, v80
	v_mul_f32_e32 v184, v8, v64
	v_mul_f32_e32 v183, v40, v64
	v_mul_f32_e32 v182, v9, v65
	v_mul_f32_e32 v181, v41, v65
	v_mul_f32_e32 v180, v10, v66
	v_mul_f32_e32 v179, v42, v66
	v_mul_f32_e32 v178, v11, v67
	v_mul_f32_e32 v176, v43, v67
	v_mul_f32_e32 v175, v12, v68
	v_mul_f32_e32 v174, v44, v68
	v_mul_f32_e32 v173, v13, v69
	v_mul_f32_e32 v172, v45, v69
	v_mul_f32_e32 v170, v14, v70
	v_mul_f32_e32 v169, v46, v70
	v_mul_f32_e32 v168, v15, v71
	v_mul_f32_e32 v167, v47, v71
	s_cbranch_vccz .LBB0_692
	v_cvt_pk_bf16_f32 v3, v246, s0
	ds_write_b16 v166, v3
	v_cvt_pk_bf16_f32 v3, v245, s0
	ds_write_b16 v166, v3 offset:64
	v_cvt_pk_bf16_f32 v3, v244, s0
	ds_write_b16 v166, v3 offset:128
	v_cvt_pk_bf16_f32 v3, v243, s0
	ds_write_b16 v166, v3 offset:192
	v_cvt_pk_bf16_f32 v3, v242, s0
	ds_write_b16 v166, v3 offset:256
	v_cvt_pk_bf16_f32 v3, v233, s0
	ds_write_b16 v166, v3 offset:320
	v_cvt_pk_bf16_f32 v3, v232, s0
	ds_write_b16 v166, v3 offset:384
	v_cvt_pk_bf16_f32 v3, v231, s0
	ds_write_b16 v166, v3 offset:448
	v_cvt_pk_bf16_f32 v3, v229, s0
	ds_write_b16 v166, v3 offset:1024
	v_cvt_pk_bf16_f32 v3, v228, s0
	ds_write_b16 v166, v3 offset:1088
	v_cvt_pk_bf16_f32 v3, v227, s0
	ds_write_b16 v166, v3 offset:1152
	v_cvt_pk_bf16_f32 v3, v226, s0
	ds_write_b16 v166, v3 offset:1216
	v_cvt_pk_bf16_f32 v3, v225, s0
	ds_write_b16 v166, v3 offset:1280
	v_cvt_pk_bf16_f32 v3, v224, s0
	ds_write_b16 v166, v3 offset:1344
	v_cvt_pk_bf16_f32 v3, v219, s0
	ds_write_b16 v166, v3 offset:1408
	v_cvt_pk_bf16_f32 v3, v218, s0
	ds_write_b16 v166, v3 offset:1472
	v_cvt_pk_bf16_f32 v3, v217, s0
	ds_write_b16 v166, v3 offset:2048
	v_cvt_pk_bf16_f32 v3, v216, s0
	ds_write_b16 v166, v3 offset:2112
	v_cvt_pk_bf16_f32 v3, v215, s0
	ds_write_b16 v166, v3 offset:2176
	v_cvt_pk_bf16_f32 v3, v214, s0
	ds_write_b16 v166, v3 offset:2240
	v_cvt_pk_bf16_f32 v3, v213, s0
	ds_write_b16 v166, v3 offset:2304
	v_cvt_pk_bf16_f32 v3, v212, s0
	ds_write_b16 v166, v3 offset:2368
	v_cvt_pk_bf16_f32 v3, v211, s0
	ds_write_b16 v166, v3 offset:2432
	v_cvt_pk_bf16_f32 v3, v210, s0
	ds_write_b16 v166, v3 offset:2496
	v_cvt_pk_bf16_f32 v3, v209, s0
	ds_write_b16 v166, v3 offset:3072
	v_cvt_pk_bf16_f32 v3, v208, s0
	ds_write_b16 v166, v3 offset:3136
	v_cvt_pk_bf16_f32 v3, v207, s0
	ds_write_b16 v166, v3 offset:3200
	v_cvt_pk_bf16_f32 v3, v206, s0
	ds_write_b16 v166, v3 offset:3264
	v_cvt_pk_bf16_f32 v3, v205, s0
	v_lshlrev_b32_e32 v0, 3, v241
	ds_write_b16 v166, v3 offset:3328
	v_cvt_pk_bf16_f32 v3, v204, s0
	v_and_b32_e32 v36, 56, v0
	ds_write_b16 v166, v3 offset:3392
	v_cvt_pk_bf16_f32 v3, v203, s0
	v_lshlrev_b32_e32 v220, 1, v36
	ds_write_b16 v166, v3 offset:3456
	v_cvt_pk_bf16_f32 v3, v202, s0
	v_add_u32_e32 v2, s74, v220
	v_lshl_add_u64 v[0:1], s[0:1], 0, v[220:221]
	ds_write_b16 v166, v3 offset:3520
	v_mov_b32_e32 v85, v221
	v_mov_b32_e32 v91, v221
	v_mov_b32_e32 v89, v221
	v_mov_b32_e32 v87, v221
	s_waitcnt lgkmcnt(0)
	v_lshl_add_u32 v3, v230, 7, v2
	v_lshl_add_u64 v[98:99], v[0:1], 0, v[84:85]
	v_lshl_add_u32 v4, v185, 7, v2
	v_lshl_add_u64 v[96:97], v[0:1], 0, v[90:91]
	v_lshl_add_u32 v5, v177, 7, v2
	v_lshl_add_u64 v[94:95], v[0:1], 0, v[88:89]
	v_lshl_add_u32 v2, v171, 7, v2
	v_lshl_add_u64 v[92:93], v[0:1], 0, v[86:87]
	v_cvt_pk_bf16_f32 v0, v201, s0
	ds_read_b128 v[62:65], v3
	ds_read_b128 v[16:19], v2
	global_load_dwordx4 v[66:69], v[98:99], off
	global_load_dwordx4 v[50:53], v[96:97], off
	ds_read_b128 v[46:49], v4
	ds_read_b128 v[38:41], v5
	global_load_dwordx4 v[42:45], v[94:95], off
	global_load_dwordx4 v[20:23], v[92:93], off
	s_waitcnt lgkmcnt(0)
	ds_write_b16 v166, v0
	v_cvt_pk_bf16_f32 v0, v200, s0
	ds_write_b16 v166, v0 offset:64
	v_cvt_pk_bf16_f32 v0, v199, s0
	ds_write_b16 v166, v0 offset:128
	v_cvt_pk_bf16_f32 v0, v198, s0
	ds_write_b16 v166, v0 offset:192
	v_cvt_pk_bf16_f32 v0, v197, s0
	ds_write_b16 v166, v0 offset:256
	v_cvt_pk_bf16_f32 v0, v196, s0
	ds_write_b16 v166, v0 offset:320
	v_cvt_pk_bf16_f32 v0, v195, s0
	ds_write_b16 v166, v0 offset:384
	v_cvt_pk_bf16_f32 v0, v194, s0
	ds_write_b16 v166, v0 offset:448
	v_cvt_pk_bf16_f32 v0, v193, s0
	ds_write_b16 v166, v0 offset:1024
	v_cvt_pk_bf16_f32 v0, v192, s0
	ds_write_b16 v166, v0 offset:1088
	v_cvt_pk_bf16_f32 v0, v191, s0
	ds_write_b16 v166, v0 offset:1152
	v_cvt_pk_bf16_f32 v0, v190, s0
	ds_write_b16 v166, v0 offset:1216
	v_cvt_pk_bf16_f32 v0, v189, s0
	ds_write_b16 v166, v0 offset:1280
	v_cvt_pk_bf16_f32 v0, v188, s0
	ds_write_b16 v166, v0 offset:1344
	v_cvt_pk_bf16_f32 v0, v187, s0
	ds_write_b16 v166, v0 offset:1408
	v_cvt_pk_bf16_f32 v0, v186, s0
	ds_write_b16 v166, v0 offset:1472
	v_cvt_pk_bf16_f32 v0, v184, s0
	ds_write_b16 v166, v0 offset:2048
	v_cvt_pk_bf16_f32 v0, v183, s0
	ds_write_b16 v166, v0 offset:2112
	v_cvt_pk_bf16_f32 v0, v182, s0
	ds_write_b16 v166, v0 offset:2176
	v_cvt_pk_bf16_f32 v0, v181, s0
	ds_write_b16 v166, v0 offset:2240
	v_cvt_pk_bf16_f32 v0, v180, s0
	ds_write_b16 v166, v0 offset:2304
	v_cvt_pk_bf16_f32 v0, v179, s0
	ds_write_b16 v166, v0 offset:2368
	v_cvt_pk_bf16_f32 v0, v178, s0
	ds_write_b16 v166, v0 offset:2432
	v_cvt_pk_bf16_f32 v0, v176, s0
	ds_write_b16 v166, v0 offset:2496
	v_cvt_pk_bf16_f32 v0, v175, s0
	ds_write_b16 v166, v0 offset:3072
	v_cvt_pk_bf16_f32 v0, v174, s0
	ds_write_b16 v166, v0 offset:3136
	v_cvt_pk_bf16_f32 v0, v173, s0
	ds_write_b16 v166, v0 offset:3200
	v_cvt_pk_bf16_f32 v0, v172, s0
	ds_write_b16 v166, v0 offset:3264
	v_cvt_pk_bf16_f32 v0, v170, s0
	ds_write_b16 v166, v0 offset:3328
	v_cvt_pk_bf16_f32 v0, v169, s0
	ds_write_b16 v166, v0 offset:3392
	v_cvt_pk_bf16_f32 v0, v168, s0
	ds_write_b16 v166, v0 offset:3456
	v_cvt_pk_bf16_f32 v0, v167, s0
	ds_write_b16 v166, v0 offset:3520
	s_waitcnt lgkmcnt(0)
	global_load_dwordx4 v[54:57], v[98:99], off offset:128
	global_load_dwordx4 v[28:31], v[96:97], off offset:128
	global_load_dwordx4 v[8:11], v[94:95], off offset:128
	s_add_u32 s24, s3, s50
	ds_read_b128 v[58:61], v3
	ds_read_b128 v[24:27], v4
	ds_read_b128 v[12:15], v5
	ds_read_b128 v[0:3], v2
	s_addc_u32 s25, s18, s51
	v_or_b32_e32 v124, s48, v230
	v_mov_b32_e32 v125, s49
	v_lshl_add_u64 v[122:123], s[24:25], 0, v[220:221]
	v_lshlrev_b64 v[32:33], 11, v[124:125]
	v_lshl_add_u64 v[70:71], v[122:123], 0, v[32:33]
	s_waitcnt lgkmcnt(3)
	v_and_b32_e32 v34, 0xffff0000, v59
	v_lshlrev_b32_e32 v35, 16, v59
	v_or_b32_e32 v124, s48, v185
	global_load_dwordx4 v[4:7], v[92:93], off offset:128
	s_waitcnt lgkmcnt(0)
	global_load_dwordx4 v[76:79], v[70:71], off
	s_waitcnt vmcnt(8)
	v_lshlrev_b32_e32 v80, 16, v68
	v_and_b32_e32 v81, 0xffff0000, v68
	v_lshlrev_b32_e32 v68, 16, v64
	v_lshlrev_b32_e32 v128, 16, v63
	v_and_b32_e32 v129, 0xffff0000, v63
	v_lshlrev_b32_e32 v144, 16, v47
	v_and_b32_e32 v145, 0xffff0000, v47
	v_lshlrev_b32_e32 v148, 16, v46
	v_and_b32_e32 v149, 0xffff0000, v46
	v_lshlrev_b32_e32 v130, 16, v48
	v_and_b32_e32 v131, 0xffff0000, v48
	v_lshlrev_b32_e32 v48, 16, v58
	s_waitcnt vmcnt(7)
	v_lshlrev_b32_e32 v142, 16, v51
	v_and_b32_e32 v143, 0xffff0000, v51
	v_lshlrev_b32_e32 v146, 16, v50
	v_and_b32_e32 v147, 0xffff0000, v50
	s_mov_b64 s[52:53], 0
	s_waitcnt vmcnt(4)
	v_and_b32_e32 v32, 0xffff0000, v55
	v_lshlrev_b32_e32 v33, 16, v55
	v_pk_fma_f32 v[108:109], v[222:223], v[34:35], v[32:33] neg_lo:[1,0,0] neg_hi:[1,0,0]
	v_and_b32_e32 v32, 0xffff0000, v56
	v_lshlrev_b32_e32 v33, 16, v56
	v_and_b32_e32 v34, 0xffff0000, v60
	v_lshlrev_b32_e32 v35, 16, v60
	v_pk_fma_f32 v[102:103], v[222:223], v[34:35], v[32:33] neg_lo:[1,0,0] neg_hi:[1,0,0]
	v_and_b32_e32 v32, 0xffff0000, v57
	v_lshlrev_b32_e32 v33, 16, v57
	v_and_b32_e32 v34, 0xffff0000, v61
	v_lshlrev_b32_e32 v35, 16, v61
	v_pk_fma_f32 v[100:101], v[222:223], v[34:35], v[32:33] neg_lo:[1,0,0] neg_hi:[1,0,0]
	v_lshlrev_b64 v[34:35], 11, v[124:125]
	v_lshl_add_u64 v[60:61], v[122:123], 0, v[34:35]
	global_load_dwordx4 v[72:75], v[60:61], off
	s_waitcnt vmcnt(4)
	v_and_b32_e32 v32, 0xffff0000, v29
	v_lshlrev_b32_e32 v33, 16, v29
	s_waitcnt lgkmcnt(2)
	v_and_b32_e32 v34, 0xffff0000, v25
	v_lshlrev_b32_e32 v35, 16, v25
	v_pk_fma_f32 v[110:111], v[222:223], v[34:35], v[32:33] neg_lo:[1,0,0] neg_hi:[1,0,0]
	v_and_b32_e32 v32, 0xffff0000, v30
	v_lshlrev_b32_e32 v33, 16, v30
	v_and_b32_e32 v34, 0xffff0000, v26
	v_lshlrev_b32_e32 v35, 16, v26
	v_and_b32_e32 v30, 0xffff0000, v31
	v_lshlrev_b32_e32 v31, 16, v31
	v_and_b32_e32 v26, 0xffff0000, v27
	v_lshlrev_b32_e32 v27, 16, v27
	v_pk_fma_f32 v[104:105], v[222:223], v[26:27], v[30:31] neg_lo:[1,0,0] neg_hi:[1,0,0]
	s_waitcnt vmcnt(3)
	v_and_b32_e32 v26, 0xffff0000, v9
	v_lshlrev_b32_e32 v27, 16, v9
	s_waitcnt lgkmcnt(1)
	v_and_b32_e32 v30, 0xffff0000, v13
	v_lshlrev_b32_e32 v31, 16, v13
	v_pk_fma_f32 v[56:57], v[222:223], v[30:31], v[26:27] neg_lo:[1,0,0] neg_hi:[1,0,0]
	v_and_b32_e32 v26, 0xffff0000, v10
	v_lshlrev_b32_e32 v27, 16, v10
	v_and_b32_e32 v30, 0xffff0000, v14
	v_lshlrev_b32_e32 v31, 16, v14
	v_and_b32_e32 v10, 0xffff0000, v11
	v_lshlrev_b32_e32 v11, 16, v11
	v_and_b32_e32 v14, 0xffff0000, v15
	v_lshlrev_b32_e32 v15, 16, v15
	v_pk_fma_f32 v[10:11], v[222:223], v[14:15], v[10:11] neg_lo:[1,0,0] neg_hi:[1,0,0]
	v_lshlrev_b32_e32 v14, 16, v69
	v_and_b32_e32 v15, 0xffff0000, v69
	v_and_b32_e32 v69, 0xffff0000, v64
	v_or_b32_e32 v124, s48, v177
	v_pk_fma_f32 v[116:117], v[222:223], v[68:69], v[80:81] neg_lo:[1,0,0] neg_hi:[1,0,0]
	v_lshlrev_b64 v[80:81], 11, v[124:125]
	v_pk_fma_f32 v[26:27], v[222:223], v[30:31], v[26:27] neg_lo:[1,0,0] neg_hi:[1,0,0]
	v_lshlrev_b32_e32 v9, 2, v36
	v_lshlrev_b32_e32 v30, 16, v65
	v_and_b32_e32 v31, 0xffff0000, v65
	v_lshl_add_u64 v[158:159], v[122:123], 0, v[80:81]
	v_pk_fma_f32 v[106:107], v[222:223], v[34:35], v[32:33] neg_lo:[1,0,0] neg_hi:[1,0,0]
	v_pk_fma_f32 v[14:15], v[222:223], v[30:31], v[14:15] neg_lo:[1,0,0] neg_hi:[1,0,0]
	global_load_dwordx4 v[30:33], v9, s[28:29] offset:16
	global_load_dwordx4 v[34:37], v9, s[28:29]
	global_load_dwordx4 v[80:83], v[158:159], off
	v_lshlrev_b32_e32 v64, 16, v67
	v_and_b32_e32 v65, 0xffff0000, v67
	v_pk_fma_f32 v[152:153], v[222:223], v[128:129], v[64:65] neg_lo:[1,0,0] neg_hi:[1,0,0]
	v_lshlrev_b32_e32 v64, 16, v66
	v_and_b32_e32 v65, 0xffff0000, v66
	v_lshlrev_b32_e32 v66, 16, v62
	v_and_b32_e32 v67, 0xffff0000, v62
	v_pk_fma_f32 v[160:161], v[222:223], v[66:67], v[64:65] neg_lo:[1,0,0] neg_hi:[1,0,0]
	v_pk_mul_f32 v[248:249], v[152:153], v[152:153]
	v_pk_mul_f32 v[250:251], v[160:161], v[160:161]
	v_pk_mul_f32 v[140:141], v[116:117], v[116:117]
	v_add_f32_e32 v13, v250, v251
	v_add_f32_e32 v13, v248, v13
	v_or_b32_e32 v124, s48, v171
	v_add_f32_e32 v13, v249, v13
	v_lshlrev_b64 v[46:47], 11, v[124:125]
	v_add_f32_e32 v13, v140, v13
	v_pk_mul_f32 v[138:139], v[14:15], v[14:15]
	v_lshlrev_b32_e32 v128, 16, v49
	v_and_b32_e32 v129, 0xffff0000, v49
	v_lshl_add_u64 v[164:165], v[122:123], 0, v[46:47]
	v_lshlrev_b32_e32 v46, 16, v54
	v_and_b32_e32 v47, 0xffff0000, v54
	v_and_b32_e32 v49, 0xffff0000, v58
	v_add_f32_e32 v13, v141, v13
	v_add_f32_e32 v13, v138, v13
	v_add_f32_e32 v13, v139, v13
	v_pk_mul_f32 v[118:119], v[108:109], v[108:109]
	v_pk_mul_f32 v[120:121], v[102:103], v[102:103]
	v_pk_mul_f32 v[126:127], v[100:101], v[100:101]
	global_load_dwordx4 v[64:67], v[164:165], off
	s_waitcnt vmcnt(5)
	v_lshlrev_b32_e32 v150, 16, v78
	v_and_b32_e32 v151, 0xffff0000, v78
	v_lshlrev_b32_e32 v154, 16, v77
	v_and_b32_e32 v155, 0xffff0000, v77
	v_lshlrev_b32_e32 v162, 16, v76
	s_waitcnt vmcnt(4)
	v_lshlrev_b32_e32 v132, 16, v74
	v_and_b32_e32 v133, 0xffff0000, v74
	v_lshlrev_b32_e32 v134, 16, v73
	v_and_b32_e32 v135, 0xffff0000, v73
	v_lshlrev_b32_e32 v136, 16, v72
	v_and_b32_e32 v137, 0xffff0000, v72
	v_lshlrev_b32_e32 v72, 16, v75
	v_and_b32_e32 v73, 0xffff0000, v75
	v_pk_fma_f32 v[74:75], v[222:223], v[48:49], v[46:47] neg_lo:[1,0,0] neg_hi:[1,0,0]
	v_and_b32_e32 v163, 0xffff0000, v76
	v_pk_mul_f32 v[46:47], v[74:75], v[74:75]
	v_lshlrev_b32_e32 v156, 16, v79
	v_add_f32_e32 v13, v13, v46
	v_add_f32_e32 v13, v47, v13
	v_add_f32_e32 v13, v119, v13
	v_add_f32_e32 v13, v118, v13
	v_add_f32_e32 v13, v121, v13
	v_add_f32_e32 v13, v120, v13
	v_add_f32_e32 v13, v127, v13
	v_add_f32_e32 v13, v126, v13
	ds_bpermute_b32 v25, v237, v13
	v_and_b32_e32 v157, 0xffff0000, v79
	v_lshlrev_b32_e32 v76, 16, v53
	v_and_b32_e32 v77, 0xffff0000, v53
	v_lshlrev_b32_e32 v78, 16, v52
	s_waitcnt lgkmcnt(0)
	v_add_f32_e32 v13, v13, v25
	ds_bpermute_b32 v25, v238, v13
	v_and_b32_e32 v79, 0xffff0000, v52
	global_load_dwordx4 v[52:55], v[158:159], off offset:128
	v_lshlrev_b32_e32 v120, 16, v41
	v_and_b32_e32 v121, 0xffff0000, v41
	s_waitcnt lgkmcnt(0)
	v_add_f32_e32 v13, v13, v25
	ds_bpermute_b32 v25, v239, v13
	v_lshlrev_b32_e32 v124, 16, v40
	v_and_b32_e32 v125, 0xffff0000, v40
	v_lshlrev_b32_e32 v122, 16, v44
	v_and_b32_e32 v123, 0xffff0000, v44
	s_waitcnt lgkmcnt(0)
	v_add_f32_e32 v13, v13, v25
	v_fmamk_f32 v13, v13, 0x3c000000, v235
	v_lshlrev_b32_e32 v118, 16, v45
	v_and_b32_e32 v119, 0xffff0000, v45
	global_load_dwordx4 v[68:71], v[70:71], off offset:128
	v_pk_fma_f32 v[78:79], v[222:223], v[130:131], v[78:79] neg_lo:[1,0,0] neg_hi:[1,0,0]
	s_waitcnt vmcnt(3)
	v_lshlrev_b32_e32 v58, 16, v82
	v_and_b32_e32 v59, 0xffff0000, v82
	v_rsq_f32_e32 v82, v13
	global_load_dwordx4 v[60:63], v[60:61], off offset:128
	v_pk_fma_f32 v[130:131], v[222:223], v[144:145], v[142:143] neg_lo:[1,0,0] neg_hi:[1,0,0]
	v_pk_fma_f32 v[144:145], v[222:223], v[148:149], v[146:147] neg_lo:[1,0,0] neg_hi:[1,0,0]
	v_pk_mul_f32 v[40:41], v[160:161], v[82:83] op_sel_hi:[1,0]
	v_pk_mul_f32 v[14:15], v[14:15], v[82:83] op_sel_hi:[1,0]
	v_pk_mul_f32 v[40:41], v[34:35], v[40:41]
	v_pk_mul_f32 v[14:15], v[14:15], v[32:33]
	v_pk_mul_f32 v[40:41], v[40:41], v[162:163]
	v_pk_mul_f32 v[14:15], v[14:15], v[156:157]
	v_cvt_pk_bf16_f32 v44, v40, v41
	v_pk_mul_f32 v[40:41], v[152:153], v[82:83] op_sel_hi:[1,0]
	v_cvt_pk_bf16_f32 v47, v14, v15
	v_pk_mul_f32 v[40:41], v[40:41], v[36:37]
	v_lshlrev_b32_e32 v152, 16, v23
	v_pk_mul_f32 v[40:41], v[40:41], v[154:155]
	v_and_b32_e32 v153, 0xffff0000, v23
	v_cvt_pk_bf16_f32 v45, v40, v41
	v_pk_mul_f32 v[40:41], v[116:117], v[82:83] op_sel_hi:[1,0]
	v_lshlrev_b32_e32 v154, 16, v19
	v_pk_mul_f32 v[40:41], v[40:41], v[30:31]
	v_and_b32_e32 v155, 0xffff0000, v19
	v_pk_mul_f32 v[40:41], v[40:41], v[150:151]
	v_lshlrev_b32_e32 v126, 16, v43
	v_cvt_pk_bf16_f32 v46, v40, v41
	global_store_dwordx4 v[98:99], v[44:47], off
	global_load_dwordx4 v[44:47], v9, s[28:29] offset:272
	s_nop 0
	global_load_dwordx4 v[48:51], v9, s[28:29] offset:256
	v_and_b32_e32 v127, 0xffff0000, v43
	v_lshlrev_b32_e32 v138, 16, v39
	v_and_b32_e32 v139, 0xffff0000, v39
	v_lshlrev_b32_e32 v140, 16, v42
	v_and_b32_e32 v141, 0xffff0000, v42
	v_lshlrev_b32_e32 v150, 16, v38
	v_and_b32_e32 v151, 0xffff0000, v38
	v_pk_fma_f32 v[148:149], v[222:223], v[154:155], v[152:153] neg_lo:[1,0,0] neg_hi:[1,0,0]
	v_pk_mul_f32 v[154:155], v[144:145], v[144:145]
	global_load_dwordx4 v[38:41], v[164:165], off offset:128
	v_lshlrev_b32_e32 v160, 16, v21
	v_and_b32_e32 v161, 0xffff0000, v21
	v_lshlrev_b32_e32 v164, 16, v20
	v_and_b32_e32 v165, 0xffff0000, v20
	v_and_b32_e32 v20, 0xffff0000, v1
	v_lshlrev_b32_e32 v21, 16, v1
	v_pk_fma_f32 v[126:127], v[222:223], v[138:139], v[126:127] neg_lo:[1,0,0] neg_hi:[1,0,0]
	v_pk_fma_f32 v[138:139], v[222:223], v[150:151], v[140:141] neg_lo:[1,0,0] neg_hi:[1,0,0]
	v_pk_mul_f32 v[150:151], v[130:131], v[130:131]
	v_add_f32_e32 v1, v154, v155
	v_lshlrev_b32_e32 v162, 16, v17
	v_and_b32_e32 v163, 0xffff0000, v17
	v_lshlrev_b32_e32 v248, 16, v16
	v_and_b32_e32 v249, 0xffff0000, v16
	v_and_b32_e32 v16, 0xffff0000, v5
	v_lshlrev_b32_e32 v17, 16, v5
	v_add_f32_e32 v1, v150, v1
	v_lshlrev_b32_e32 v116, 16, v81
	v_and_b32_e32 v117, 0xffff0000, v81
	v_lshlrev_b32_e32 v42, 16, v80
	v_and_b32_e32 v43, 0xffff0000, v80
	s_waitcnt vmcnt(7)
	v_lshlrev_b32_e32 v80, 16, v65
	v_and_b32_e32 v81, 0xffff0000, v65
	v_lshlrev_b32_e32 v250, 16, v64
	v_and_b32_e32 v251, 0xffff0000, v64
	v_pk_fma_f32 v[20:21], v[222:223], v[20:21], v[16:17] neg_lo:[1,0,0] neg_hi:[1,0,0]
	v_lshlrev_b32_e32 v64, 16, v28
	v_and_b32_e32 v65, 0xffff0000, v28
	v_and_b32_e32 v16, 0xffff0000, v6
	v_lshlrev_b32_e32 v17, 16, v6
	v_and_b32_e32 v28, 0xffff0000, v2
	v_lshlrev_b32_e32 v29, 16, v2
	v_pk_mul_f32 v[140:141], v[78:79], v[78:79]
	v_add_f32_e32 v1, v151, v1
	v_pk_fma_f32 v[16:17], v[222:223], v[28:29], v[16:17] neg_lo:[1,0,0] neg_hi:[1,0,0]
	v_lshlrev_b32_e32 v28, 16, v24
	v_and_b32_e32 v29, 0xffff0000, v24
	v_pk_fma_f32 v[24:25], v[222:223], v[128:129], v[76:77] neg_lo:[1,0,0] neg_hi:[1,0,0]
	v_add_f32_e32 v1, v140, v1
	v_lshlrev_b32_e32 v156, 16, v22
	v_and_b32_e32 v157, 0xffff0000, v22
	v_lshlrev_b32_e32 v158, 16, v18
	v_and_b32_e32 v159, 0xffff0000, v18
	v_lshlrev_b32_e32 v18, 16, v66
	v_and_b32_e32 v19, 0xffff0000, v66
	v_lshlrev_b32_e32 v22, 16, v67
	v_and_b32_e32 v23, 0xffff0000, v67
	v_pk_mul_f32 v[66:67], v[24:25], v[24:25]
	v_add_f32_e32 v1, v141, v1
	v_pk_fma_f32 v[28:29], v[222:223], v[28:29], v[64:65] neg_lo:[1,0,0] neg_hi:[1,0,0]
	v_add_f32_e32 v1, v66, v1
	v_add_f32_e32 v1, v67, v1
	v_pk_mul_f32 v[64:65], v[28:29], v[28:29]
	v_pk_mul_f32 v[112:113], v[110:111], v[110:111]
	v_add_f32_e32 v1, v1, v64
	v_add_f32_e32 v1, v65, v1
	v_add_f32_e32 v1, v113, v1
	v_pk_mul_f32 v[114:115], v[106:107], v[106:107]
	v_add_f32_e32 v1, v112, v1
	v_and_b32_e32 v6, 0xffff0000, v7
	v_lshlrev_b32_e32 v7, 16, v7
	v_and_b32_e32 v2, 0xffff0000, v3
	v_lshlrev_b32_e32 v3, 16, v3
	v_add_f32_e32 v1, v115, v1
	v_pk_fma_f32 v[2:3], v[222:223], v[2:3], v[6:7] neg_lo:[1,0,0] neg_hi:[1,0,0]
	v_pk_mul_f32 v[6:7], v[104:105], v[104:105]
	v_add_f32_e32 v1, v114, v1
	v_add_f32_e32 v1, v7, v1
	v_add_f32_e32 v1, v6, v1
	ds_bpermute_b32 v5, v237, v1
	v_pk_mul_f32 v[6:7], v[102:103], v[82:83] op_sel_hi:[1,0]
	v_pk_mul_f32 v[108:109], v[108:109], v[82:83] op_sel_hi:[1,0]
	s_waitcnt vmcnt(2)
	v_pk_mul_f32 v[6:7], v[6:7], v[44:45] op_sel:[1,0] op_sel_hi:[0,1]
	v_lshlrev_b32_e32 v66, 16, v70
	s_waitcnt lgkmcnt(0)
	v_add_f32_e32 v1, v1, v5
	ds_bpermute_b32 v5, v238, v1
	v_and_b32_e32 v67, 0xffff0000, v70
	v_pk_fma_f32 v[152:153], v[222:223], v[158:159], v[156:157] neg_lo:[1,0,0] neg_hi:[1,0,0]
	v_pk_fma_f32 v[156:157], v[222:223], v[162:163], v[160:161] neg_lo:[1,0,0] neg_hi:[1,0,0]
	v_lshlrev_b32_e32 v162, 16, v68
	s_waitcnt lgkmcnt(0)
	v_add_f32_e32 v1, v1, v5
	ds_bpermute_b32 v5, v239, v1
	v_and_b32_e32 v163, 0xffff0000, v68
	s_waitcnt vmcnt(1)
	v_pk_mul_f32 v[108:109], v[108:109], v[50:51] op_sel:[1,0] op_sel_hi:[0,1]
	v_lshlrev_b32_e32 v68, 16, v69
	v_and_b32_e32 v69, 0xffff0000, v69
	s_waitcnt lgkmcnt(0)
	v_add_f32_e32 v1, v1, v5
	v_fmamk_f32 v1, v1, 0x3c000000, v235
	v_pk_mul_f32 v[6:7], v[6:7], v[66:67]
	v_rsq_f32_e32 v70, v1
	v_pk_mul_f32 v[68:69], v[108:109], v[68:69]
	v_cvt_pk_bf16_f32 v66, v6, v7
	v_pk_mul_f32 v[6:7], v[100:101], v[82:83] op_sel_hi:[1,0]
	v_cvt_pk_bf16_f32 v65, v68, v69
	v_pk_mul_f32 v[6:7], v[6:7], v[46:47] op_sel:[1,0] op_sel_hi:[0,1]
	v_lshlrev_b32_e32 v68, 16, v71
	v_and_b32_e32 v69, 0xffff0000, v71
	v_pk_mul_f32 v[74:75], v[74:75], v[82:83] op_sel_hi:[1,0]
	v_pk_mul_f32 v[6:7], v[6:7], v[68:69]
	v_pk_mul_f32 v[74:75], v[74:75], v[48:49]
	v_cvt_pk_bf16_f32 v67, v6, v7
	v_pk_mul_f32 v[6:7], v[144:145], v[70:71] op_sel_hi:[1,0]
	v_pk_mul_f32 v[74:75], v[74:75], v[162:163]
	v_pk_mul_f32 v[6:7], v[34:35], v[6:7]
	v_cvt_pk_bf16_f32 v64, v74, v75
	v_pk_mul_f32 v[6:7], v[6:7], v[136:137]
	global_store_dwordx4 v[98:99], v[64:67], off offset:128
	v_pk_mul_f32 v[154:155], v[138:139], v[138:139]
	v_pk_mul_f32 v[162:163], v[126:127], v[126:127]
	v_cvt_pk_bf16_f32 v64, v6, v7
	v_pk_mul_f32 v[6:7], v[130:131], v[70:71] op_sel_hi:[1,0]
	v_add_f32_e32 v1, v154, v155
	v_pk_mul_f32 v[6:7], v[36:37], v[6:7]
	v_pk_fma_f32 v[122:123], v[222:223], v[124:125], v[122:123] neg_lo:[1,0,0] neg_hi:[1,0,0]
	v_pk_mul_f32 v[6:7], v[6:7], v[134:135]
	v_add_f32_e32 v1, v162, v1
	v_cvt_pk_bf16_f32 v65, v6, v7
	v_pk_mul_f32 v[6:7], v[78:79], v[70:71] op_sel_hi:[1,0]
	v_pk_mul_f32 v[108:109], v[122:123], v[122:123]
	v_pk_mul_f32 v[6:7], v[6:7], v[30:31]
	v_add_f32_e32 v1, v163, v1
	v_pk_mul_f32 v[6:7], v[6:7], v[132:133]
	v_pk_fma_f32 v[118:119], v[222:223], v[120:121], v[118:119] neg_lo:[1,0,0] neg_hi:[1,0,0]
	v_cvt_pk_bf16_f32 v66, v6, v7
	v_pk_mul_f32 v[6:7], v[24:25], v[70:71] op_sel_hi:[1,0]
	v_add_f32_e32 v1, v108, v1
	v_pk_mul_f32 v[6:7], v[6:7], v[32:33]
	v_pk_mul_f32 v[158:159], v[118:119], v[118:119]
	v_pk_mul_f32 v[6:7], v[6:7], v[72:73]
	v_lshlrev_b32_e32 v24, 16, v60
	v_cvt_pk_bf16_f32 v67, v6, v7
	v_pk_mul_f32 v[6:7], v[28:29], v[70:71] op_sel_hi:[1,0]
	v_and_b32_e32 v25, 0xffff0000, v60
	v_lshlrev_b32_e32 v28, 16, v61
	v_and_b32_e32 v29, 0xffff0000, v61
	v_lshlrev_b32_e32 v60, 16, v8
	v_and_b32_e32 v61, 0xffff0000, v8
	v_lshlrev_b32_e32 v8, 16, v12
	v_and_b32_e32 v9, 0xffff0000, v12
	v_add_f32_e32 v1, v109, v1
	v_pk_fma_f32 v[12:13], v[222:223], v[8:9], v[60:61] neg_lo:[1,0,0] neg_hi:[1,0,0]
	v_add_f32_e32 v1, v158, v1
	v_pk_mul_f32 v[8:9], v[12:13], v[12:13]
	v_add_f32_e32 v1, v159, v1
	v_add_f32_e32 v1, v1, v8
	v_pk_mul_f32 v[76:77], v[56:57], v[56:57]
	v_add_f32_e32 v1, v9, v1
	v_add_f32_e32 v1, v77, v1
	v_pk_mul_f32 v[128:129], v[26:27], v[26:27]
	v_add_f32_e32 v1, v76, v1
	v_add_f32_e32 v1, v129, v1
	v_pk_mul_f32 v[142:143], v[10:11], v[10:11]
	v_add_f32_e32 v1, v128, v1
	v_add_f32_e32 v1, v143, v1
	v_add_f32_e32 v1, v142, v1
	ds_bpermute_b32 v5, v237, v1
	v_pk_mul_f32 v[6:7], v[6:7], v[48:49]
	v_lshlrev_b32_e32 v14, 16, v83
	v_pk_mul_f32 v[6:7], v[6:7], v[24:25]
	v_pk_mul_f32 v[24:25], v[110:111], v[70:71] op_sel_hi:[1,0]
	s_waitcnt lgkmcnt(0)
	v_add_f32_e32 v1, v1, v5
	ds_bpermute_b32 v5, v238, v1
	v_pk_mul_f32 v[24:25], v[24:25], v[50:51] op_sel:[1,0] op_sel_hi:[0,1]
	v_pk_mul_f32 v[8:9], v[24:25], v[28:29]
	v_cvt_pk_bf16_f32 v6, v6, v7
	v_cvt_pk_bf16_f32 v7, v8, v9
	s_waitcnt lgkmcnt(0)
	v_add_f32_e32 v1, v1, v5
	ds_bpermute_b32 v5, v239, v1
	v_pk_mul_f32 v[8:9], v[106:107], v[70:71] op_sel_hi:[1,0]
	v_lshlrev_b32_e32 v24, 16, v62
	v_pk_mul_f32 v[8:9], v[8:9], v[44:45] op_sel:[1,0] op_sel_hi:[0,1]
	v_and_b32_e32 v25, 0xffff0000, v62
	s_waitcnt lgkmcnt(0)
	v_add_f32_e32 v1, v1, v5
	v_fmamk_f32 v1, v1, 0x3c000000, v235
	v_pk_mul_f32 v[8:9], v[8:9], v[24:25]
	v_pk_mul_f32 v[24:25], v[104:105], v[70:71] op_sel_hi:[1,0]
	v_rsq_f32_e32 v60, v1
	v_pk_mul_f32 v[24:25], v[24:25], v[46:47] op_sel:[1,0] op_sel_hi:[0,1]
	v_lshlrev_b32_e32 v28, 16, v63
	v_and_b32_e32 v29, 0xffff0000, v63
	v_pk_mul_f32 v[24:25], v[24:25], v[28:29]
	v_cvt_pk_bf16_f32 v8, v8, v9
	v_cvt_pk_bf16_f32 v9, v24, v25
	global_store_dwordx4 v[96:97], v[6:9], off offset:128
	v_pk_mul_f32 v[24:25], v[118:119], v[60:61] op_sel_hi:[1,0]
	v_and_b32_e32 v15, 0xffff0000, v83
	v_pk_mul_f32 v[6:7], v[138:139], v[60:61] op_sel_hi:[1,0]
	v_pk_mul_f32 v[8:9], v[126:127], v[60:61] op_sel_hi:[1,0]
	v_pk_mul_f32 v[6:7], v[34:35], v[6:7]
	v_pk_mul_f32 v[8:9], v[36:37], v[8:9]
	v_pk_mul_f32 v[6:7], v[6:7], v[42:43]
	v_pk_mul_f32 v[8:9], v[8:9], v[116:117]
	v_cvt_pk_bf16_f32 v6, v6, v7
	v_cvt_pk_bf16_f32 v7, v8, v9
	v_pk_mul_f32 v[8:9], v[122:123], v[60:61] op_sel_hi:[1,0]
	v_pk_mul_f32 v[24:25], v[24:25], v[32:33]
	v_pk_mul_f32 v[8:9], v[30:31], v[8:9]
	v_pk_mul_f32 v[14:15], v[24:25], v[14:15]
	v_pk_mul_f32 v[8:9], v[8:9], v[58:59]
	v_pk_fma_f32 v[160:161], v[222:223], v[248:249], v[164:165] neg_lo:[1,0,0] neg_hi:[1,0,0]
	v_cvt_pk_bf16_f32 v8, v8, v9
	v_cvt_pk_bf16_f32 v9, v14, v15
	global_store_dwordx4 v[94:95], v[6:9], off
	v_pk_mul_f32 v[112:113], v[160:161], v[160:161]
	v_pk_mul_f32 v[164:165], v[156:157], v[156:157]
	v_pk_mul_f32 v[6:7], v[12:13], v[60:61] op_sel_hi:[1,0]
	v_lshlrev_b32_e32 v8, 16, v52
	v_pk_mul_f32 v[6:7], v[6:7], v[48:49]
	v_and_b32_e32 v9, 0xffff0000, v52
	v_pk_mul_f32 v[6:7], v[6:7], v[8:9]
	v_pk_mul_f32 v[140:141], v[152:153], v[152:153]
	v_cvt_pk_bf16_f32 v6, v6, v7
	v_add_f32_e32 v7, v112, v113
	v_add_f32_e32 v7, v164, v7
	v_add_f32_e32 v7, v165, v7
	v_add_f32_e32 v7, v140, v7
	v_pk_mul_f32 v[150:151], v[148:149], v[148:149]
	v_lshlrev_b32_e32 v14, 16, v4
	v_and_b32_e32 v15, 0xffff0000, v4
	v_lshlrev_b32_e32 v4, 16, v0
	v_and_b32_e32 v5, 0xffff0000, v0
	v_add_f32_e32 v7, v141, v7
	v_pk_fma_f32 v[0:1], v[222:223], v[4:5], v[14:15] neg_lo:[1,0,0] neg_hi:[1,0,0]
	v_add_f32_e32 v7, v150, v7
	v_pk_mul_f32 v[4:5], v[0:1], v[0:1]
	v_add_f32_e32 v7, v151, v7
	v_add_f32_e32 v4, v7, v4
	v_pk_mul_f32 v[146:147], v[20:21], v[20:21]
	v_add_f32_e32 v4, v5, v4
	v_add_f32_e32 v4, v147, v4
	v_pk_mul_f32 v[120:121], v[16:17], v[16:17]
	v_add_f32_e32 v4, v146, v4
	v_add_f32_e32 v4, v121, v4
	v_pk_mul_f32 v[124:125], v[2:3], v[2:3]
	v_add_f32_e32 v4, v120, v4
	v_add_f32_e32 v4, v125, v4
	v_add_f32_e32 v14, v124, v4
	ds_bpermute_b32 v15, v237, v14
	v_pk_mul_f32 v[8:9], v[56:57], v[60:61] op_sel_hi:[1,0]
	v_lshlrev_b32_e32 v12, 16, v53
	v_pk_mul_f32 v[8:9], v[8:9], v[50:51] op_sel:[1,0] op_sel_hi:[0,1]
	v_and_b32_e32 v13, 0xffff0000, v53
	v_pk_mul_f32 v[4:5], v[8:9], v[12:13]
	s_waitcnt lgkmcnt(0)
	v_add_f32_e32 v12, v14, v15
	ds_bpermute_b32 v13, v238, v12
	v_cvt_pk_bf16_f32 v7, v4, v5
	v_pk_mul_f32 v[4:5], v[26:27], v[60:61] op_sel_hi:[1,0]
	v_lshlrev_b32_e32 v8, 16, v54
	v_pk_mul_f32 v[4:5], v[4:5], v[44:45] op_sel:[1,0] op_sel_hi:[0,1]
	v_and_b32_e32 v9, 0xffff0000, v54
	v_pk_mul_f32 v[4:5], v[4:5], v[8:9]
	s_waitcnt lgkmcnt(0)
	v_add_f32_e32 v9, v12, v13
	ds_bpermute_b32 v12, v239, v9
	v_cvt_pk_bf16_f32 v8, v4, v5
	v_pk_mul_f32 v[4:5], v[10:11], v[60:61] op_sel_hi:[1,0]
	v_lshlrev_b32_e32 v10, 16, v55
	v_pk_mul_f32 v[4:5], v[4:5], v[46:47] op_sel:[1,0] op_sel_hi:[0,1]
	s_waitcnt lgkmcnt(0)
	v_add_f32_e32 v9, v9, v12
	v_fmamk_f32 v9, v9, 0x3c000000, v235
	v_rsq_f32_e32 v12, v9
	v_and_b32_e32 v11, 0xffff0000, v55
	v_pk_mul_f32 v[4:5], v[4:5], v[10:11]
	global_store_dwordx4 v[96:97], v[64:67], off
	v_cvt_pk_bf16_f32 v9, v4, v5
	global_store_dwordx4 v[94:95], v[6:9], off offset:128
	v_pk_mul_f32 v[4:5], v[160:161], v[12:13] op_sel_hi:[1,0]
	v_pk_mul_f32 v[0:1], v[0:1], v[12:13] op_sel_hi:[1,0]
	v_pk_mul_f32 v[6:7], v[156:157], v[12:13] op_sel_hi:[1,0]
	v_pk_mul_f32 v[4:5], v[34:35], v[4:5]
	v_pk_mul_f32 v[6:7], v[36:37], v[6:7]
	v_pk_mul_f32 v[4:5], v[4:5], v[250:251]
	v_pk_mul_f32 v[6:7], v[6:7], v[80:81]
	v_cvt_pk_bf16_f32 v4, v4, v5
	v_cvt_pk_bf16_f32 v5, v6, v7
	v_pk_mul_f32 v[6:7], v[152:153], v[12:13] op_sel_hi:[1,0]
	v_pk_mul_f32 v[8:9], v[148:149], v[12:13] op_sel_hi:[1,0]
	v_pk_mul_f32 v[6:7], v[30:31], v[6:7]
	v_pk_mul_f32 v[8:9], v[32:33], v[8:9]
	v_pk_mul_f32 v[6:7], v[6:7], v[18:19]
	v_pk_mul_f32 v[8:9], v[8:9], v[22:23]
	v_cvt_pk_bf16_f32 v6, v6, v7
	v_cvt_pk_bf16_f32 v7, v8, v9
	global_store_dwordx4 v[92:93], v[4:7], off
	v_pk_mul_f32 v[0:1], v[0:1], v[48:49]
	s_waitcnt vmcnt(6)
	v_lshlrev_b32_e32 v4, 16, v38
	v_and_b32_e32 v5, 0xffff0000, v38
	v_pk_mul_f32 v[0:1], v[0:1], v[4:5]
	v_lshlrev_b32_e32 v6, 16, v39
	v_cvt_pk_bf16_f32 v4, v0, v1
	v_pk_mul_f32 v[0:1], v[20:21], v[12:13] op_sel_hi:[1,0]
	v_and_b32_e32 v7, 0xffff0000, v39
	v_pk_mul_f32 v[0:1], v[0:1], v[50:51] op_sel:[1,0] op_sel_hi:[0,1]
	v_pk_mul_f32 v[0:1], v[0:1], v[6:7]
	v_lshlrev_b32_e32 v6, 16, v40
	v_cvt_pk_bf16_f32 v5, v0, v1
	v_pk_mul_f32 v[0:1], v[16:17], v[12:13] op_sel_hi:[1,0]
	v_and_b32_e32 v7, 0xffff0000, v40
	v_pk_mul_f32 v[0:1], v[0:1], v[44:45] op_sel:[1,0] op_sel_hi:[0,1]
	v_pk_mul_f32 v[0:1], v[0:1], v[6:7]
	s_nop 0
	v_cvt_pk_bf16_f32 v6, v0, v1
	v_pk_mul_f32 v[0:1], v[2:3], v[12:13] op_sel_hi:[1,0]
	v_lshlrev_b32_e32 v2, 16, v41
	v_pk_mul_f32 v[0:1], v[0:1], v[46:47] op_sel:[1,0] op_sel_hi:[0,1]
	v_and_b32_e32 v3, 0xffff0000, v41
	v_pk_mul_f32 v[0:1], v[0:1], v[2:3]
	s_nop 0
	v_cvt_pk_bf16_f32 v7, v0, v1
	global_store_dwordx4 v[92:93], v[4:7], off offset:128
